# diff fast loop-back: m0 values and fast/slow decision computed before the barrier
# baseline (speedup 1.0000x reference)
; DI void diff_pass(const bf16_t* __restrict__ qrow  , const bf16_t* __restrict__ kg, const bf16_t* __restrict__ vg,
;                   int nkt, int q0, float negM2, f32x16 (&O)[4], float& lsum, char* lds) {
;     ...
;         char* st = lds + (kt & 1) * 24576;
;         if (kt + 1 < nkt) {
;             char* st2 = lds + ((kt + 1) & 1) * 24576 + wb;
;             __builtin_amdgcn_global_load_lds((const unsigned*)(kgs + (size_t)(kt + 1) * 64 * 512), (lds_ptr_t)(st2), 16, 0, 0);
;             __builtin_amdgcn_global_load_lds((const unsigned*)(vgs + (kt + 1) * 64), (lds_ptr_t)(st2 + 8192), 16, 0, 0);
;             __builtin_amdgcn_global_load_lds((const unsigned*)(vgs + (size_t)64 * kS + (kt + 1) * 64), (lds_ptr_t)(st2 + 16384), 16, 0, 0);
;         }
;         __builtin_amdgcn_sched_barrier(0);
;         if (kt * 64 <= q0 + 31) {
;             f32x16 Sx[2];
;             {
;                 bf16x8 kf[2][4];
; #pragma unroll
;                 for (int kb = 0; kb < 2; ++kb)
; #pragma unroll
;                     for (int ks = 0; ks < 4; ++ks) kf[kb][ks] = *(const bf16x8*)(st + (32 * kb + l31) * 128 + (((2 * ks + h) ^ f) << 4));
;                 __builtin_amdgcn_sched_barrier(0);
; #pragma unroll
;                 for (int ks = 0; ks < 4; ++ks)
; #pragma unroll
;                     for (int kb = 0; kb < 2; ++kb) Sx[kb] = ks == 0 ? MFMA(kf[kb][0], qf[0], minit) : MFMA(kf[kb][ks], qf[ks], Sx[kb]);
;             }
;             if (kt * 64 + 63 > q0) {
; #pragma unroll
;                 for (int kb = 0; kb < 2; ++kb)
; #pragma unroll
;                     for (int i = 0; i < 16; ++i) {
;                         float p = fexp2(Sx[kb][i]);
;                         const int key = kt * 64 + 32 * kb + (i & 3) + 8 * (i >> 2) + 4 * h;
;                         if (key > qpos) p = 0.f;
;                         lsum += p; Sx[kb][i] = p;
;                     }
;             } else {
;                 float l0 = 0.f, l1 = 0.f;
; #pragma unroll
;                 for (int i = 0; i < 16; ++i) { const float p0 = fexp2(Sx[0][i]), p1 = fexp2(Sx[1][i]); l0 += p0; l1 += p1; Sx[0][i] = p0; Sx[1][i] = p1; }
;                 lsum += l0 + l1;
;             }
;             bf16x8 pf[4];
;             pf[0] = pack8(Sx[0], 0); pf[1] = pack8(Sx[0], 1); pf[2] = pack8(Sx[1], 0); pf[3] = pack8(Sx[1], 1);
;             {
;                 bf16x8 vf[2][4];
; #pragma unroll
.Ldf_fast:
	ds_read_b128 v[2:5], v195
	ds_read_b128 v[10:13], v194
	ds_read_b128 v[200:203], v193
	ds_read_b128 v[208:211], v0
	ds_read_b128 v[6:9], v195 offset:4096
	ds_read_b128 v[196:199], v194 offset:4096
	ds_read_b128 v[204:207], v193 offset:4096
	ds_read_b128 v[212:215], v0 offset:4096
	v_mov_b32_e32 v14, 0
	v_mov_b32_e32 v15, 0
	s_waitcnt lgkmcnt(7)
	v_mfma_f32_32x32x16_bf16 v[96:111], v[2:5], v[140:143], v[16:31]
	s_waitcnt lgkmcnt(6)
	v_mfma_f32_32x32x16_bf16 v[96:111], v[10:13], v[136:139], v[96:111]
	s_waitcnt lgkmcnt(5)
	v_mfma_f32_32x32x16_bf16 v[96:111], v[200:203], v[132:135], v[96:111]
	s_waitcnt lgkmcnt(4)
	v_mfma_f32_32x32x16_bf16 v[96:111], v[208:211], v[128:131], v[96:111]
	s_waitcnt lgkmcnt(3)
	v_mfma_f32_32x32x16_bf16 v[112:127], v[6:9], v[140:143], v[16:31]
	ds_read_b128 v[2:5], v195 offset:8192
	ds_read_b128 v[10:13], v195 offset:12288
	s_waitcnt lgkmcnt(4)
	v_mfma_f32_32x32x16_bf16 v[112:127], v[196:199], v[136:139], v[112:127]
	ds_read_b128 v[200:203], v195 offset:16384
	ds_read_b128 v[208:211], v195 offset:20480
	s_nop 3
	v_exp_f32_e32 v96, v96
	v_exp_f32_e32 v97, v97
	v_add_f32_e32 v14, v14, v96
	v_add_f32_e32 v14, v14, v97
	s_waitcnt lgkmcnt(5)
	v_mfma_f32_32x32x16_bf16 v[112:127], v[204:207], v[132:135], v[112:127]
	v_exp_f32_e32 v98, v98
	v_exp_f32_e32 v99, v99
	v_add_f32_e32 v14, v14, v98
	v_add_f32_e32 v14, v14, v99
	s_waitcnt lgkmcnt(4)
	v_mfma_f32_32x32x16_bf16 v[112:127], v[212:215], v[128:131], v[112:127]
	v_exp_f32_e32 v100, v100
	v_exp_f32_e32 v101, v101
	v_add_f32_e32 v14, v14, v100
	v_add_f32_e32 v14, v14, v101
	v_exp_f32_e32 v102, v102
	v_exp_f32_e32 v103, v103
	v_add_f32_e32 v14, v14, v102
	v_add_f32_e32 v14, v14, v103
	v_cvt_pk_bf16_f32 v96, v96, v97
	v_cvt_pk_bf16_f32 v97, v98, v99
	v_cvt_pk_bf16_f32 v98, v100, v101
	v_cvt_pk_bf16_f32 v99, v102, v103
	s_waitcnt lgkmcnt(3)
	s_nop 0
	v_mfma_f32_32x32x16_bf16 v[80:95], v[2:5], v[96:99], v[80:95]
	ds_read_b128 v[6:9], v194 offset:8192
	ds_read_b128 v[196:199], v194 offset:12288
	ds_read_b128 v[204:207], v194 offset:16384
	ds_read_b128 v[212:215], v194 offset:20480
	v_exp_f32_e32 v104, v104
	v_exp_f32_e32 v105, v105
	v_add_f32_e32 v14, v14, v104
	v_add_f32_e32 v14, v14, v105
	s_waitcnt lgkmcnt(6)
	v_mfma_f32_32x32x16_bf16 v[64:79], v[10:13], v[96:99], v[64:79]
	ds_read_b128 v[2:5], v193 offset:8192
	v_exp_f32_e32 v106, v106
	v_exp_f32_e32 v107, v107
	v_add_f32_e32 v14, v14, v106
	v_add_f32_e32 v14, v14, v107
	s_waitcnt lgkmcnt(6)
	v_mfma_f32_32x32x16_bf16 v[48:63], v[200:203], v[96:99], v[48:63]
	ds_read_b128 v[10:13], v193 offset:12288
	v_exp_f32_e32 v108, v108
	v_exp_f32_e32 v109, v109
	v_add_f32_e32 v14, v14, v108
	v_add_f32_e32 v14, v14, v109
	s_waitcnt lgkmcnt(6)
	v_mfma_f32_32x32x16_bf16 v[32:47], v[208:211], v[96:99], v[32:47]
	ds_read_b128 v[200:203], v193 offset:16384
	v_exp_f32_e32 v110, v110
	v_exp_f32_e32 v111, v111
	v_add_f32_e32 v14, v14, v110
	v_add_f32_e32 v14, v14, v111
	v_cvt_pk_bf16_f32 v104, v104, v105
	v_cvt_pk_bf16_f32 v105, v106, v107
	v_cvt_pk_bf16_f32 v106, v108, v109
	v_cvt_pk_bf16_f32 v107, v110, v111
	s_waitcnt lgkmcnt(6)
	s_nop 0
	v_mfma_f32_32x32x16_bf16 v[80:95], v[6:9], v[104:107], v[80:95]
	ds_read_b128 v[208:211], v193 offset:20480
	v_exp_f32_e32 v112, v112
	v_exp_f32_e32 v113, v113
	v_add_f32_e32 v15, v15, v112
	v_add_f32_e32 v15, v15, v113
	s_waitcnt lgkmcnt(6)
	v_mfma_f32_32x32x16_bf16 v[64:79], v[196:199], v[104:107], v[64:79]
	ds_read_b128 v[6:9], v0 offset:8192
	v_exp_f32_e32 v114, v114
	v_exp_f32_e32 v115, v115
	v_add_f32_e32 v15, v15, v114
	v_add_f32_e32 v15, v15, v115
	s_waitcnt lgkmcnt(6)
	v_mfma_f32_32x32x16_bf16 v[48:63], v[204:207], v[104:107], v[48:63]
	ds_read_b128 v[196:199], v0 offset:12288
	v_exp_f32_e32 v116, v116
	v_exp_f32_e32 v117, v117
	v_add_f32_e32 v15, v15, v116
	v_add_f32_e32 v15, v15, v117
	s_waitcnt lgkmcnt(6)
	v_mfma_f32_32x32x16_bf16 v[32:47], v[212:215], v[104:107], v[32:47]
	ds_read_b128 v[204:207], v0 offset:16384
	v_exp_f32_e32 v118, v118
	v_exp_f32_e32 v119, v119
	v_add_f32_e32 v15, v15, v118
	v_add_f32_e32 v15, v15, v119
	v_cvt_pk_bf16_f32 v112, v112, v113
	v_cvt_pk_bf16_f32 v113, v114, v115
	v_cvt_pk_bf16_f32 v114, v116, v117
	v_cvt_pk_bf16_f32 v115, v118, v119
	s_waitcnt lgkmcnt(6)
	s_nop 0
	v_mfma_f32_32x32x16_bf16 v[80:95], v[2:5], v[112:115], v[80:95]
	ds_read_b128 v[212:215], v0 offset:20480
	s_and_b32 s0, 1, s54
	s_cselect_b32 s0, 0x6000, 0
	s_xor_b32 s1, s0, 0x6000
	v_or_b32_e32 v0, s0, v188
	v_readfirstlane_b32 s32, v187
	v_add_u32_e32 v195, v0, v189
	v_add_u32_e32 v194, v0, v190
	v_add_u32_e32 v193, v0, v191
	v_add_u32_e32 v0, v0, v192
	s_mov_b64 s[28:29], 0x10000
	v_lshl_add_u64 v[216:217], v[160:161], 0, v[158:159]
	v_lshl_add_u64 v[218:219], v[164:165], 0, v[158:159]
	v_lshl_add_u64 v[216:217], v[216:217], 0, s[28:29]
	s_mov_b64 s[28:29], 0x1b800100
	v_lshl_add_u64 v[220:221], v[218:219], 0, s[28:29]
	s_mov_b64 s[28:29], 0x1b900100
	v_lshl_add_u64 v[218:219], v[218:219], 0, s[28:29]
	v_exp_f32_e32 v120, v120
	v_exp_f32_e32 v121, v121
	v_add_f32_e32 v15, v15, v120
	v_add_f32_e32 v15, v15, v121
	s_waitcnt lgkmcnt(6)
	v_mfma_f32_32x32x16_bf16 v[64:79], v[10:13], v[112:115], v[64:79]
	v_exp_f32_e32 v122, v122
	v_exp_f32_e32 v123, v123
	v_add_f32_e32 v15, v15, v122
	v_add_f32_e32 v15, v15, v123
	s_waitcnt lgkmcnt(5)
	v_mfma_f32_32x32x16_bf16 v[48:63], v[200:203], v[112:115], v[48:63]
	v_exp_f32_e32 v124, v124
	v_exp_f32_e32 v125, v125
	v_add_f32_e32 v15, v15, v124
	v_add_f32_e32 v15, v15, v125
	s_waitcnt lgkmcnt(4)
	v_mfma_f32_32x32x16_bf16 v[32:47], v[208:211], v[112:115], v[32:47]
	v_exp_f32_e32 v126, v126
	v_exp_f32_e32 v127, v127
	v_add_f32_e32 v15, v15, v126
	v_add_f32_e32 v15, v15, v127
	v_cvt_pk_bf16_f32 v120, v120, v121
	v_cvt_pk_bf16_f32 v121, v122, v123
	v_cvt_pk_bf16_f32 v122, v124, v125
	v_cvt_pk_bf16_f32 v123, v126, v127
	v_add_f32_e32 v14, v14, v15
	s_waitcnt lgkmcnt(3)
	v_mfma_f32_32x32x16_bf16 v[80:95], v[6:9], v[120:123], v[80:95]
	v_add_f32_e32 v186, v186, v14
	s_waitcnt lgkmcnt(2)
	v_mfma_f32_32x32x16_bf16 v[64:79], v[196:199], v[120:123], v[64:79]
	s_waitcnt lgkmcnt(1)
	v_mfma_f32_32x32x16_bf16 v[48:63], v[204:207], v[120:123], v[48:63]
	s_waitcnt lgkmcnt(0)
	v_mfma_f32_32x32x16_bf16 v[32:47], v[212:215], v[120:123], v[32:47]
	s_waitcnt vmcnt(0)
	s_add_i32 s55, s55, 64
	s_add_i32 s54, s54, 1
	s_mov_b64 s[28:29], 0x10000
	v_lshl_add_u64 v[164:165], v[164:165], 0, s[18:19]
	v_lshl_add_u64 v[160:161], v[160:161], 0, s[28:29]
	s_add_i32 s28, s1, s32
	s_add_i32 s29, s28, 0x2000
	s_add_i32 s0, s28, 0x4000
	s_add_i32 s30, s55, 63
	v_cmp_le_i32_e32 vcc, s30, v148
	s_cmp_eq_u32 s35, s55
	s_waitcnt lgkmcnt(0)
	s_barrier
	s_cbranch_scc1 .LBB0_93
	s_mov_b32 m0, s28
	s_and_b32 s30, 1, s54
	global_load_lds_dwordx4 v[216:217], off
	s_mov_b32 m0, s29
	s_nop 0
	global_load_lds_dwordx4 v[220:221], off
	s_mov_b32 m0, s0
	s_nop 0
	global_load_lds_dwordx4 v[218:219], off
	s_cbranch_vccnz .Ldf_fast
	s_branch .Ldf_slow_entry
